# LDS-DMA loops: ds_reads woven into the M0-write to DMA-load gaps instead of s_nop
# speedup vs baseline: 1.0093x; 1.0025x over previous
.Lf2_stage0:
	ds_read_b128 v[66:69], v130 offset:0
	ds_read_b128 v[70:73], v130 offset:4096
	ds_read_b128 v[74:77], v134 offset:16384
	ds_read_b128 v[78:81], v134 offset:20480
	s_cmp_ge_u32 s22, 43
	s_cbranch_scc1 .Lf2_nl0
	s_add_u32 m0, s38, 0x8000
	ds_read_b128 v[82:85], v131 offset:0
	global_load_lds_dwordx4 v152, s[10:11]
	s_add_u32 m0, s38, 0xc000
	ds_read_b128 v[86:89], v131 offset:4096
	global_load_lds_dwordx4 v152, s[8:9]
	s_add_u32 m0, s38, 0x9000
	ds_read_b128 v[90:93], v135 offset:16384
	global_load_lds_dwordx4 v150, s[10:11]
	s_add_u32 m0, s38, 0xd000
	ds_read_b128 v[94:97], v135 offset:20480
	global_load_lds_dwordx4 v150, s[8:9]
	s_add_u32 m0, s38, 0xa000
	ds_read_b128 v[98:101], v132 offset:0
	global_load_lds_dwordx4 v148, s[10:11]
	s_add_u32 m0, s38, 0xe000
	ds_read_b128 v[102:105], v132 offset:4096
	global_load_lds_dwordx4 v148, s[8:9]
	s_add_u32 m0, s38, 0xb000
	ds_read_b128 v[106:109], v136 offset:16384
	global_load_lds_dwordx4 v146, s[10:11]
	s_add_u32 m0, s38, 0xf000
	ds_read_b128 v[110:113], v136 offset:20480
	global_load_lds_dwordx4 v146, s[8:9]
	s_add_u32 s8, s8, 0x80
	s_addc_u32 s9, s9, 0
	s_add_u32 s10, s10, 0x80
	s_addc_u32 s11, s11, 0
	s_branch .Lf2_dd0
.Lf2_nl0:
	ds_read_b128 v[82:85], v131 offset:0
	ds_read_b128 v[86:89], v131 offset:4096
	ds_read_b128 v[90:93], v135 offset:16384
	ds_read_b128 v[94:97], v135 offset:20480
	ds_read_b128 v[98:101], v132 offset:0
	ds_read_b128 v[102:105], v132 offset:4096
	ds_read_b128 v[106:109], v136 offset:16384
	ds_read_b128 v[110:113], v136 offset:20480

.Lf2_stage1:
	ds_read_b128 v[66:69], v130 offset:32768
	ds_read_b128 v[70:73], v130 offset:36864
	ds_read_b128 v[74:77], v134 offset:49152
	ds_read_b128 v[78:81], v134 offset:53248
	s_cmp_ge_u32 s22, 43
	s_cbranch_scc1 .Lf2_nl1
	s_add_u32 m0, s38, 0x0
	ds_read_b128 v[82:85], v131 offset:32768
	global_load_lds_dwordx4 v152, s[10:11]
	s_add_u32 m0, s38, 0x4000
	ds_read_b128 v[86:89], v131 offset:36864
	global_load_lds_dwordx4 v152, s[8:9]
	s_add_u32 m0, s38, 0x1000
	ds_read_b128 v[90:93], v135 offset:49152
	global_load_lds_dwordx4 v150, s[10:11]
	s_add_u32 m0, s38, 0x5000
	ds_read_b128 v[94:97], v135 offset:53248
	global_load_lds_dwordx4 v150, s[8:9]
	s_add_u32 m0, s38, 0x2000
	ds_read_b128 v[98:101], v132 offset:32768
	global_load_lds_dwordx4 v148, s[10:11]
	s_add_u32 m0, s38, 0x6000
	ds_read_b128 v[102:105], v132 offset:36864
	global_load_lds_dwordx4 v148, s[8:9]
	s_add_u32 m0, s38, 0x3000
	ds_read_b128 v[106:109], v136 offset:49152
	global_load_lds_dwordx4 v146, s[10:11]
	s_add_u32 m0, s38, 0x7000
	ds_read_b128 v[110:113], v136 offset:53248
	global_load_lds_dwordx4 v146, s[8:9]
	s_add_u32 s8, s8, 0x80
	s_addc_u32 s9, s9, 0
	s_add_u32 s10, s10, 0x80
	s_addc_u32 s11, s11, 0
	s_branch .Lf2_dd1
.Lf2_nl1:
	ds_read_b128 v[82:85], v131 offset:32768
	ds_read_b128 v[86:89], v131 offset:36864
	ds_read_b128 v[90:93], v135 offset:49152
	ds_read_b128 v[94:97], v135 offset:53248
	ds_read_b128 v[98:101], v132 offset:32768
	ds_read_b128 v[102:105], v132 offset:36864
	ds_read_b128 v[106:109], v136 offset:49152
	ds_read_b128 v[110:113], v136 offset:53248

.Lfg_stage0:
	ds_read_b128 v[178:181], v130 offset:0
	ds_read_b128 v[182:185], v130 offset:2048
	ds_read_b128 v[186:189], v130 offset:4096
	ds_read_b128 v[190:193], v130 offset:6144
	ds_read_b128 v[194:197], v132 offset:16384
	ds_read_b128 v[198:201], v132 offset:18432
	s_cmp_ge_u32 s13, 31
	s_cbranch_scc1 .Lfg_nl0
	s_add_u32 m0, s18, 0x6000
	ds_read_b128 v[216:219], v131 offset:0
	global_load_lds_dwordx4 v139, s[14:15]
	s_add_u32 m0, s18, 0x7000
	ds_read_b128 v[220:223], v131 offset:2048
	global_load_lds_dwordx4 v140, s[14:15]
	s_add_u32 m0, s18, 0x8000
	ds_read_b128 v[226:229], v131 offset:4096
	global_load_lds_dwordx4 v141, s[14:15]
	s_add_u32 m0, s18, 0x9000
	ds_read_b128 v[230:233], v131 offset:6144
	global_load_lds_dwordx4 v142, s[14:15]
	s_add_u32 m0, s18, 0xa000
	ds_read_b128 v[234:237], v133 offset:16384
	global_load_lds_dwordx4 v143, s[16:17]
	s_add_u32 m0, s18, 0xb000
	ds_read_b128 v[240:243], v133 offset:18432
	global_load_lds_dwordx4 v144, s[16:17]
	s_add_u32 s14, s14, 64
	s_addc_u32 s15, s15, 0
	s_add_u32 s16, s16, 64
	s_addc_u32 s17, s17, 0
	s_branch .Lfg_dd0
.Lfg_nl0:
	ds_read_b128 v[216:219], v131 offset:0
	ds_read_b128 v[220:223], v131 offset:2048
	ds_read_b128 v[226:229], v131 offset:4096
	ds_read_b128 v[230:233], v131 offset:6144
	ds_read_b128 v[234:237], v133 offset:16384
	ds_read_b128 v[240:243], v133 offset:18432

.Lfg_stage1:
	ds_read_b128 v[178:181], v130 offset:24576
	ds_read_b128 v[182:185], v130 offset:26624
	ds_read_b128 v[186:189], v130 offset:28672
	ds_read_b128 v[190:193], v130 offset:30720
	ds_read_b128 v[194:197], v132 offset:40960
	ds_read_b128 v[198:201], v132 offset:43008
	s_cmp_ge_u32 s13, 31
	s_cbranch_scc1 .Lfg_nl1
	s_add_u32 m0, s18, 0x0
	ds_read_b128 v[216:219], v131 offset:24576
	global_load_lds_dwordx4 v139, s[14:15]
	s_add_u32 m0, s18, 0x1000
	ds_read_b128 v[220:223], v131 offset:26624
	global_load_lds_dwordx4 v140, s[14:15]
	s_add_u32 m0, s18, 0x2000
	ds_read_b128 v[226:229], v131 offset:28672
	global_load_lds_dwordx4 v141, s[14:15]
	s_add_u32 m0, s18, 0x3000
	ds_read_b128 v[230:233], v131 offset:30720
	global_load_lds_dwordx4 v142, s[14:15]
	s_add_u32 m0, s18, 0x4000
	ds_read_b128 v[234:237], v133 offset:40960
	global_load_lds_dwordx4 v143, s[16:17]
	s_add_u32 m0, s18, 0x5000
	ds_read_b128 v[240:243], v133 offset:43008
	global_load_lds_dwordx4 v144, s[16:17]
	s_add_u32 s14, s14, 64
	s_addc_u32 s15, s15, 0
	s_add_u32 s16, s16, 64
	s_addc_u32 s17, s17, 0
	s_branch .Lfg_dd1
.Lfg_nl1:
	ds_read_b128 v[216:219], v131 offset:24576
	ds_read_b128 v[220:223], v131 offset:26624
	ds_read_b128 v[226:229], v131 offset:28672
	ds_read_b128 v[230:233], v131 offset:30720
	ds_read_b128 v[234:237], v133 offset:40960
	ds_read_b128 v[240:243], v133 offset:43008

.Lwo_stage0:
	ds_read_b128 v[66:69], v130 offset:0
	ds_read_b128 v[70:73], v130 offset:4096
	ds_read_b128 v[74:77], v134 offset:16384
	ds_read_b128 v[78:81], v134 offset:20480
	s_cmp_ge_u32 s22, 15
	s_cbranch_scc1 .Lwo_nl0
	s_add_u32 m0, s38, 0x8000
	ds_read_b128 v[82:85], v131 offset:0
	global_load_lds_dwordx4 v152, s[10:11]
	s_add_u32 m0, s38, 0xc000
	ds_read_b128 v[86:89], v131 offset:4096
	global_load_lds_dwordx4 v152, s[8:9]
	s_add_u32 m0, s38, 0x9000
	ds_read_b128 v[90:93], v135 offset:16384
	global_load_lds_dwordx4 v150, s[10:11]
	s_add_u32 m0, s38, 0xd000
	ds_read_b128 v[94:97], v135 offset:20480
	global_load_lds_dwordx4 v150, s[8:9]
	s_add_u32 m0, s38, 0xa000
	ds_read_b128 v[98:101], v132 offset:0
	global_load_lds_dwordx4 v148, s[10:11]
	s_add_u32 m0, s38, 0xe000
	ds_read_b128 v[102:105], v132 offset:4096
	global_load_lds_dwordx4 v148, s[8:9]
	s_add_u32 m0, s38, 0xb000
	ds_read_b128 v[106:109], v136 offset:16384
	global_load_lds_dwordx4 v146, s[10:11]
	s_add_u32 m0, s38, 0xf000
	ds_read_b128 v[110:113], v136 offset:20480
	global_load_lds_dwordx4 v146, s[8:9]
	s_add_u32 s8, s8, 0x80
	s_addc_u32 s9, s9, 0
	s_add_u32 s10, s10, 0x80
	s_addc_u32 s11, s11, 0
	s_branch .Lwo_dd0

.Lwo_stage1:
	ds_read_b128 v[66:69], v130 offset:32768
	ds_read_b128 v[70:73], v130 offset:36864
	ds_read_b128 v[74:77], v134 offset:49152
	ds_read_b128 v[78:81], v134 offset:53248
	s_cmp_ge_u32 s22, 15
	s_cbranch_scc1 .Lwo_nl1
	s_add_u32 m0, s38, 0x0
	ds_read_b128 v[82:85], v131 offset:32768
	global_load_lds_dwordx4 v152, s[10:11]
	s_add_u32 m0, s38, 0x4000
	ds_read_b128 v[86:89], v131 offset:36864
	global_load_lds_dwordx4 v152, s[8:9]
	s_add_u32 m0, s38, 0x1000
	ds_read_b128 v[90:93], v135 offset:49152
	global_load_lds_dwordx4 v150, s[10:11]
	s_add_u32 m0, s38, 0x5000
	ds_read_b128 v[94:97], v135 offset:53248
	global_load_lds_dwordx4 v150, s[8:9]
	s_add_u32 m0, s38, 0x2000
	ds_read_b128 v[98:101], v132 offset:32768
	global_load_lds_dwordx4 v148, s[10:11]
	s_add_u32 m0, s38, 0x6000
	ds_read_b128 v[102:105], v132 offset:36864
	global_load_lds_dwordx4 v148, s[8:9]
	s_add_u32 m0, s38, 0x3000
	ds_read_b128 v[106:109], v136 offset:49152
	global_load_lds_dwordx4 v146, s[10:11]
	s_add_u32 m0, s38, 0x7000
	ds_read_b128 v[110:113], v136 offset:53248
	global_load_lds_dwordx4 v146, s[8:9]
	s_add_u32 s8, s8, 0x80
	s_addc_u32 s9, s9, 0
	s_add_u32 s10, s10, 0x80
	s_addc_u32 s11, s11, 0
	s_branch .Lwo_dd1

.Lpg_stage0:
	ds_read_b128 v[178:181], v130 offset:0
	ds_read_b128 v[182:185], v130 offset:2048
	ds_read_b128 v[186:189], v130 offset:4096
	ds_read_b128 v[190:193], v130 offset:6144
	ds_read_b128 v[194:197], v132 offset:16384
	ds_read_b128 v[198:201], v132 offset:18432
	s_cmp_ge_u32 s1, 31
	s_cbranch_scc1 .Lpg_nl0
	s_add_u32 m0, s18, 0x6000
	ds_read_b128 v[216:219], v131 offset:0
	global_load_lds_dwordx4 v139, s[4:5]
	s_add_u32 m0, s18, 0x7000
	ds_read_b128 v[220:223], v131 offset:2048
	global_load_lds_dwordx4 v140, s[4:5]
	s_add_u32 m0, s18, 0x8000
	ds_read_b128 v[226:229], v131 offset:4096
	global_load_lds_dwordx4 v141, s[4:5]
	s_add_u32 m0, s18, 0x9000
	ds_read_b128 v[230:233], v131 offset:6144
	global_load_lds_dwordx4 v142, s[4:5]
	s_add_u32 m0, s18, 0xa000
	ds_read_b128 v[234:237], v133 offset:16384
	global_load_lds_dwordx4 v143, s[6:7]
	s_add_u32 m0, s18, 0xb000
	ds_read_b128 v[240:243], v133 offset:18432
	global_load_lds_dwordx4 v144, s[6:7]
	s_add_u32 s4, s4, 64
	s_addc_u32 s5, s5, 0
	s_add_u32 s6, s6, 64
	s_addc_u32 s7, s7, 0
	s_branch .Lpg_dd0

.Lpg_stage1:
	ds_read_b128 v[178:181], v130 offset:24576
	ds_read_b128 v[182:185], v130 offset:26624
	ds_read_b128 v[186:189], v130 offset:28672
	ds_read_b128 v[190:193], v130 offset:30720
	ds_read_b128 v[194:197], v132 offset:40960
	ds_read_b128 v[198:201], v132 offset:43008
	s_cmp_ge_u32 s1, 31
	s_cbranch_scc1 .Lpg_nl1
	s_add_u32 m0, s18, 0x0
	ds_read_b128 v[216:219], v131 offset:24576
	global_load_lds_dwordx4 v139, s[4:5]
	s_add_u32 m0, s18, 0x1000
	ds_read_b128 v[220:223], v131 offset:26624
	global_load_lds_dwordx4 v140, s[4:5]
	s_add_u32 m0, s18, 0x2000
	ds_read_b128 v[226:229], v131 offset:28672
	global_load_lds_dwordx4 v141, s[4:5]
	s_add_u32 m0, s18, 0x3000
	ds_read_b128 v[230:233], v131 offset:30720
	global_load_lds_dwordx4 v142, s[4:5]
	s_add_u32 m0, s18, 0x4000
	ds_read_b128 v[234:237], v133 offset:40960
	global_load_lds_dwordx4 v143, s[6:7]
	s_add_u32 m0, s18, 0x5000
	ds_read_b128 v[240:243], v133 offset:43008
	global_load_lds_dwordx4 v144, s[6:7]
	s_add_u32 s4, s4, 64
	s_addc_u32 s5, s5, 0
	s_add_u32 s6, s6, 64
	s_addc_u32 s7, s7, 0
	s_branch .Lpg_dd1
